# grid barrier: per-XCD arrive atomic issued first, L2 invalidate + LDS reads + reciprocal under its round trip
# speedup vs baseline: 1.0553x; 1.0039x over previous
.LBB0_1024:
	s_waitcnt vmcnt(0)
	s_waitcnt vmcnt(0) lgkmcnt(0)
	s_barrier
	s_and_saveexec_b64 s[6:7], s[52:53]
	s_cbranch_execz .LBB0_1078
	s_getreg_b32 s0, hwreg(HW_REG_XCC_ID, 0, 4)
	s_and_b32 s0, s0, 15
	s_lshl_b32 s2, s0, 8
	s_add_u32 s2, s2, 0x494b000
	s_add_u32 s8, s90, s2
	s_addc_u32 s9, s91, 0
	v_mov_b32_e32 v165, 1
	v_mov_b32_e32 v166, 0x1000
	global_atomic_add v165, v166, v165, s[8:9] offset:1024 sc0
	buffer_inv sc1
	v_readlane_b32 s1, v255, 10
	v_mov_b32_e32 v0, s1
	ds_read_b32 v2, v0
	v_readlane_b32 s1, v255, 11
	s_waitcnt lgkmcnt(0)
	v_cmp_ne_u32_e32 vcc, 0, v2
	v_mov_b32_e32 v0, s1
	ds_read_b32 v0, v0
	s_cbranch_vccnz .LBB0_1042
	s_add_u32 s8, s90, 0x494b200
	s_addc_u32 s9, s91, 0
	s_add_u32 s10, s90, 0x494b400
	s_addc_u32 s11, s91, 0
	s_add_u32 s12, s90, 0x494b500
	s_addc_u32 s13, s91, 0
	s_add_u32 s16, s90, 0x494b600
	s_addc_u32 s17, s91, 0
	s_add_u32 s18, s90, 0x494b700
	s_addc_u32 s19, s91, 0
	s_add_u32 s20, s90, 0x494b800
	s_addc_u32 s21, s91, 0
	s_add_u32 s22, s90, 0x494b900
	s_addc_u32 s23, s91, 0
	s_add_u32 s24, s90, 0x494ba00
	s_addc_u32 s25, s91, 0
	s_add_u32 s28, s90, 0x494bb00
	s_addc_u32 s29, s91, 0
	s_add_u32 s36, s90, 0x494bc00
	s_addc_u32 s37, s91, 0
	s_add_u32 s58, s90, 0x494bd00
	s_addc_u32 s59, s91, 0
	s_add_u32 s62, s90, 0x494be00
	s_addc_u32 s63, s91, 0
	s_add_u32 s66, s90, 0x494bf00
	s_addc_u32 s67, s91, 0
	s_add_u32 s72, s90, 0x494c000
	s_addc_u32 s73, s91, 0
	s_add_u32 s74, s90, 0x494c100
	s_addc_u32 s75, s91, 0
	s_add_u32 s88, s90, 0x494c200
	s_addc_u32 s89, s91, 0
	s_add_u32 s92, s90, 0x494c300
	s_addc_u32 s93, s91, 0
	s_mov_b32 s4, 1
	s_branch .LBB0_1028

.LBB0_1042:
	v_cvt_f32_u32_e32 v4, v2
	v_sub_u32_e32 v3, 0, v2
	v_rcp_iflag_f32_e32 v4, v4
	s_nop 0
	v_mul_f32_e32 v4, 0x4f7ffffe, v4
	v_cvt_u32_f32_e32 v4, v4
	v_mul_lo_u32 v1, v3, v4
	v_mul_hi_u32 v1, v4, v1
	v_add_u32_e32 v1, v4, v1
	s_waitcnt vmcnt(0)
	v_mov_b32_e32 v5, v165
	v_mul_hi_u32 v1, v5, v1
	v_mul_lo_u32 v3, v1, v2
	v_sub_u32_e32 v3, v5, v3
	v_add_u32_e32 v4, 1, v1
	v_cmp_ge_u32_e32 vcc, v3, v2
	s_nop 1
	v_cndmask_b32_e32 v1, v1, v4, vcc
	v_sub_u32_e32 v4, v3, v2
	v_cndmask_b32_e32 v3, v3, v4, vcc
	v_add_u32_e32 v4, 1, v1
	v_cmp_ge_u32_e32 vcc, v3, v2
	v_add_u32_e32 v3, 1, v5
	s_nop 0
	v_cndmask_b32_e32 v1, v1, v4, vcc
	v_mul_lo_u32 v4, v2, v1
	v_add_u32_e32 v2, v4, v2
	v_cmp_ne_u32_e32 vcc, v3, v2
	s_waitcnt lgkmcnt(0)
	v_mad_u32_u24 v5, v1, v0, v0
	s_add_u32 s10, s90, 0x494e400
	s_addc_u32 s11, s91, 0
	s_cbranch_vccnz .Lgb_poll
	buffer_wbl2 sc1
	s_waitcnt vmcnt(0)
	v_mov_b32_e32 v2, 1
	global_atomic_add v159, v2, s[10:11]
